# v16fp8x128
# speedup vs baseline: 1.0078x; 1.0078x over previous
; #define PG8_STAGE(bufoff, gbase, ...) PG8_STAGE2(bufoff, gbase, __VA_ARGS__)
; #define PG8_WAIT_V(n) asm volatile("s_waitcnt vmcnt(" #n ")" ::: "memory")
; #define PG8_WAIT_L(n) asm volatile("s_waitcnt lgkmcnt(" #n ")" ::: "memory")
; #define PG8_BAR __builtin_amdgcn_s_barrier()
; #define PG8_SCHED __builtin_amdgcn_sched_barrier(0)
;     ...
;             PG8_LDB(B0, 0, 0); PG8_LDB(B1, 0, 1); PG8_SCHED; PG8_LDA(At, 0, 0); PG8_STAGE(PG8_SA(1, 1), a1 + hA, voffA);
;             PG8_WAIT_V(8); PG8_WAIT_L(0); PG8_BAR; PG8_MMA(0, 0, At, B0); PG8_MMA(0, 1, At, B1); PG8_BAR; PG8_SCHED;
;             PG8_LDA(At, 0, 1); PG8_STAGE(PG8_SB(0, 0), b2, voffB); PG8_STAGE(PG8_SB(0, 1), b2 + hB, voffB); PG8_STAGE(PG8_SA(0, 0), a2, voffA);
;             PG8_WAIT_V(8); PG8_WAIT_L(0); PG8_BAR; PG8_MMA(1, 0, At, B0); PG8_MMA(1, 1, At, B1); PG8_BAR; PG8_SCHED;
;             PG8_LDB(B0, 1, 0); PG8_LDB(B1, 1, 1); PG8_SCHED; PG8_LDA(At, 1, 0); PG8_STAGE(PG8_SA(0, 1), a2 + hA, voffA);
;             PG8_WAIT_V(8); PG8_WAIT_L(0); PG8_BAR; PG8_MMA(0, 0, At, B0); PG8_MMA(0, 1, At, B1); PG8_BAR; PG8_SCHED;
;             PG8_LDA(At, 1, 1); PG8_STAGE(PG8_SB(1, 0), b3, voffB); PG8_STAGE(PG8_SB(1, 1), b3 + hB, voffB); PG8_STAGE(PG8_SA(1, 0), a3, voffA);
;             PG8_WAIT_V(8); PG8_WAIT_L(0); PG8_BAR; PG8_MMA(1, 0, At, B0); PG8_MMA(1, 1, At, B1); PG8_BAR; PG8_SCHED;
.LBB0_283:
	s_add_u32 s86, s84, 0x100
	s_addc_u32 s87, s85, 0
	s_add_i32 s34, 0, 0x10000
	s_cmp_eq_u32 vcc_lo, 4
	s_cselect_b32 s89, s1, s87
	s_cselect_b32 s88, s12, s86
	s_cselect_b32 s91, s13, s83
	s_cselect_b32 s90, s51, s65
	s_add_i32 s35, 0, 0x14000
	v_add_u32_e32 v130, s34, v170
	v_add_u32_e32 v138, s35, v170
	s_waitcnt vmcnt(0)
	ds_read_b128 v[154:157], v130
	ds_read_b128 v[158:161], v130 offset:16
	ds_read_b128 v[146:149], v130 offset:2048
	ds_read_b128 v[150:153], v130 offset:2064
	ds_read_b128 v[130:133], v138 offset:2048
	ds_read_b128 v[134:137], v138 offset:2064
	ds_read_b128 v[142:145], v138 offset:16
	ds_read_b128 v[138:141], v138
	v_lshl_add_u64 v[196:197], s[84:85], 0, v[164:165]
	v_lshl_add_u64 v[166:167], v[196:197], 0, s[26:27]
	s_add_i32 m0, s97, 0xc000
	ds_read_b128 v[172:175], v171
	ds_read_b128 v[176:179], v171 offset:16
	ds_read_b128 v[180:183], v171 offset:2048
	ds_read_b128 v[184:187], v171 offset:2064
	ds_read_b128 v[188:191], v171 offset:4096
	ds_read_b128 v[192:195], v171 offset:4112
	ds_read_b128 v[200:203], v171 offset:6144
	ds_read_b128 v[204:207], v171 offset:6160
	global_load_lds_dwordx4 v[166:167], off
	v_lshl_add_u64 v[196:197], v[196:197], 0, s[72:73]
	s_add_i32 m0, s97, 0xe000
	s_nop 0
	global_load_lds_dwordx4 v[196:197], off
	s_waitcnt vmcnt(8)
	s_waitcnt lgkmcnt(0)
	s_barrier
	s_setprio 1
	s_waitcnt lgkmcnt(0)
	v_mfma_f32_16x16x128_f8f6f4 v[126:129], v[154:161], v[172:179], v[126:129]
	v_mfma_f32_16x16x128_f8f6f4 v[122:125], v[146:153], v[172:179], v[122:125]
	v_mfma_f32_16x16x128_f8f6f4 v[110:113], v[154:161], v[180:187], v[110:113]
	v_mfma_f32_16x16x128_f8f6f4 v[106:109], v[146:153], v[180:187], v[106:109]
	v_mfma_f32_16x16x128_f8f6f4 v[94:97], v[154:161], v[188:195], v[94:97]
	v_mfma_f32_16x16x128_f8f6f4 v[90:93], v[146:153], v[188:195], v[90:93]
	v_mfma_f32_16x16x128_f8f6f4 v[78:81], v[154:161], v[200:207], v[78:81]
	v_mfma_f32_16x16x128_f8f6f4 v[74:77], v[146:153], v[200:207], v[74:77]
	s_setprio 0
	s_setprio 1
	v_mfma_f32_16x16x128_f8f6f4 v[118:121], v[138:145], v[172:179], v[118:121]
	v_mfma_f32_16x16x128_f8f6f4 v[114:117], v[130:137], v[172:179], v[114:117]
	v_mfma_f32_16x16x128_f8f6f4 v[102:105], v[138:145], v[180:187], v[102:105]
	v_mfma_f32_16x16x128_f8f6f4 v[98:101], v[130:137], v[180:187], v[98:101]
	v_mfma_f32_16x16x128_f8f6f4 v[86:89], v[138:145], v[188:195], v[86:89]
	v_mfma_f32_16x16x128_f8f6f4 v[82:85], v[130:137], v[188:195], v[82:85]
	v_mfma_f32_16x16x128_f8f6f4 v[70:73], v[138:145], v[200:207], v[70:73]
	v_mfma_f32_16x16x128_f8f6f4 v[66:69], v[130:137], v[200:207], v[66:69]
	s_setprio 0
	s_barrier
	s_add_i32 s34, s34, s96
	v_lshl_add_u64 v[166:167], s[90:91], 0, v[0:1]
	s_mov_b32 m0, s34
	s_waitcnt vmcnt(0)
	ds_read_b128 v[172:175], v171 offset:16384
	ds_read_b128 v[176:179], v171 offset:16400
	ds_read_b128 v[180:183], v171 offset:18432
	ds_read_b128 v[184:187], v171 offset:18448
	ds_read_b128 v[188:191], v171 offset:20480
	ds_read_b128 v[192:195], v171 offset:20496
	ds_read_b128 v[200:203], v171 offset:22528
	ds_read_b128 v[204:207], v171 offset:22544
	global_load_lds_dwordx4 v[166:167], off
	v_lshl_add_u64 v[168:169], v[166:167], 0, s[92:93]
	s_add_i32 m0, s34, 0x2000
	s_add_i32 s34, s35, s96
	global_load_lds_dwordx4 v[168:169], off
	v_lshl_add_u64 v[168:169], v[166:167], 0, s[20:21]
	s_mov_b32 m0, s34
	s_nop 0
	global_load_lds_dwordx4 v[168:169], off
	v_lshl_add_u64 v[168:169], v[166:167], 0, s[94:95]
	s_add_i32 m0, s34, 0x2000
	s_nop 0
	global_load_lds_dwordx4 v[168:169], off
	v_lshl_add_u64 v[168:169], s[88:89], 0, v[162:163]
	s_mov_b32 m0, s97
	v_lshl_add_u64 v[196:197], v[168:169], 0, s[92:93]
	global_load_lds_dwordx4 v[168:169], off
	s_mov_b32 m0, s80
	s_nop 0
	global_load_lds_dwordx4 v[196:197], off
	s_waitcnt vmcnt(8)
	s_waitcnt lgkmcnt(0)
	s_barrier
	s_setprio 1
	s_waitcnt lgkmcnt(0)
	v_mfma_f32_16x16x128_f8f6f4 v[62:65], v[154:161], v[172:179], v[62:65]
	v_mfma_f32_16x16x128_f8f6f4 v[58:61], v[146:153], v[172:179], v[58:61]
	v_mfma_f32_16x16x128_f8f6f4 v[46:49], v[154:161], v[180:187], v[46:49]
	v_mfma_f32_16x16x128_f8f6f4 v[42:45], v[146:153], v[180:187], v[42:45]
	v_mfma_f32_16x16x128_f8f6f4 v[30:33], v[154:161], v[188:195], v[30:33]
	v_mfma_f32_16x16x128_f8f6f4 v[26:29], v[146:153], v[188:195], v[26:29]
	v_mfma_f32_16x16x128_f8f6f4 v[14:17], v[154:161], v[200:207], v[14:17]
	v_mfma_f32_16x16x128_f8f6f4 v[10:13], v[146:153], v[200:207], v[10:13]
	s_setprio 0
	s_setprio 1
	v_mfma_f32_16x16x128_f8f6f4 v[54:57], v[138:145], v[172:179], v[54:57]
	v_mfma_f32_16x16x128_f8f6f4 v[50:53], v[130:137], v[172:179], v[50:53]
	v_mfma_f32_16x16x128_f8f6f4 v[38:41], v[138:145], v[180:187], v[38:41]
	v_mfma_f32_16x16x128_f8f6f4 v[34:37], v[130:137], v[180:187], v[34:37]
	v_mfma_f32_16x16x128_f8f6f4 v[22:25], v[138:145], v[188:195], v[22:25]
	v_mfma_f32_16x16x128_f8f6f4 v[18:21], v[130:137], v[188:195], v[18:21]
	v_mfma_f32_16x16x128_f8f6f4 v[6:9], v[138:145], v[200:207], v[6:9]
	v_mfma_f32_16x16x128_f8f6f4 v[2:5], v[130:137], v[200:207], v[2:5]
	s_setprio 0
	s_barrier
; #define PG8_STAGE(bufoff, gbase, ...) PG8_STAGE2(bufoff, gbase, __VA_ARGS__)
; #define PG8_WAIT_V(n) asm volatile("s_waitcnt vmcnt(" #n ")" ::: "memory")
; #define PG8_WAIT_L(n) asm volatile("s_waitcnt lgkmcnt(" #n ")" ::: "memory")
; #define PG8_BAR __builtin_amdgcn_s_barrier()
; #define PG8_SCHED __builtin_amdgcn_sched_barrier(0)
;     ...
;             PG8_LDB(B0, 0, 0); PG8_LDB(B1, 0, 1); PG8_SCHED; PG8_LDA(At, 0, 0); PG8_STAGE(PG8_SA(1, 1), a1 + hA, voffA);
;             PG8_WAIT_V(8); PG8_WAIT_L(0); PG8_BAR; PG8_MMA(0, 0, At, B0); PG8_MMA(0, 1, At, B1); PG8_BAR; PG8_SCHED;
;             PG8_LDA(At, 0, 1); PG8_STAGE(PG8_SB(0, 0), b2, voffB); PG8_STAGE(PG8_SB(0, 1), b2 + hB, voffB); PG8_STAGE(PG8_SA(0, 0), a2, voffA);
;             PG8_WAIT_V(8); PG8_WAIT_L(0); PG8_BAR; PG8_MMA(1, 0, At, B0); PG8_MMA(1, 1, At, B1); PG8_BAR; PG8_SCHED;
;             PG8_LDB(B0, 1, 0); PG8_LDB(B1, 1, 1); PG8_SCHED; PG8_LDA(At, 1, 0); PG8_STAGE(PG8_SA(0, 1), a2 + hA, voffA);
;             PG8_WAIT_V(8); PG8_WAIT_L(0); PG8_BAR; PG8_MMA(0, 0, At, B0); PG8_MMA(0, 1, At, B1); PG8_BAR; PG8_SCHED;
;             PG8_LDA(At, 1, 1); PG8_STAGE(PG8_SB(1, 0), b3, voffB); PG8_STAGE(PG8_SB(1, 1), b3 + hB, voffB); PG8_STAGE(PG8_SA(1, 0), a3, voffA);
;             PG8_WAIT_V(8); PG8_WAIT_L(0); PG8_BAR; PG8_MMA(1, 0, At, B0); PG8_MMA(1, 1, At, B1); PG8_BAR; PG8_SCHED;
	s_add_i32 s34, 0, 0x18000
	s_add_i32 s35, 0, 0x1c000
	v_add_u32_e32 v130, s34, v170
	v_add_u32_e32 v138, s35, v170
	s_waitcnt vmcnt(0)
	ds_read_b128 v[154:157], v130
	ds_read_b128 v[158:161], v130 offset:16
	ds_read_b128 v[146:149], v130 offset:2048
	ds_read_b128 v[150:153], v130 offset:2064
	ds_read_b128 v[130:133], v138 offset:2048
	ds_read_b128 v[134:137], v138 offset:2064
	ds_read_b128 v[142:145], v138 offset:16
	ds_read_b128 v[138:141], v138
	s_mov_b32 m0, s53
	v_lshl_add_u64 v[196:197], v[168:169], 0, s[20:21]
	ds_read_b128 v[172:175], v171 offset:32768
	ds_read_b128 v[176:179], v171 offset:32784
	ds_read_b128 v[180:183], v171 offset:34816
	ds_read_b128 v[184:187], v171 offset:34832
	ds_read_b128 v[188:191], v171 offset:36864
	ds_read_b128 v[192:195], v171 offset:36880
	ds_read_b128 v[200:203], v171 offset:38912
	ds_read_b128 v[204:207], v171 offset:38928
	global_load_lds_dwordx4 v[196:197], off
	v_lshl_add_u64 v[196:197], v[168:169], 0, s[94:95]
	s_mov_b32 m0, s42
	s_nop 0
	global_load_lds_dwordx4 v[196:197], off
	s_waitcnt vmcnt(8)
	s_waitcnt lgkmcnt(0)
	s_barrier
	s_setprio 1
	s_waitcnt lgkmcnt(0)
	v_mfma_f32_16x16x128_f8f6f4 v[126:129], v[154:161], v[172:179], v[126:129]
	v_mfma_f32_16x16x128_f8f6f4 v[122:125], v[146:153], v[172:179], v[122:125]
	v_mfma_f32_16x16x128_f8f6f4 v[110:113], v[154:161], v[180:187], v[110:113]
	v_mfma_f32_16x16x128_f8f6f4 v[106:109], v[146:153], v[180:187], v[106:109]
	v_mfma_f32_16x16x128_f8f6f4 v[94:97], v[154:161], v[188:195], v[94:97]
	v_mfma_f32_16x16x128_f8f6f4 v[90:93], v[146:153], v[188:195], v[90:93]
	v_mfma_f32_16x16x128_f8f6f4 v[78:81], v[154:161], v[200:207], v[78:81]
	v_mfma_f32_16x16x128_f8f6f4 v[74:77], v[146:153], v[200:207], v[74:77]
	s_setprio 0
	s_setprio 1
	v_mfma_f32_16x16x128_f8f6f4 v[118:121], v[138:145], v[172:179], v[118:121]
	v_mfma_f32_16x16x128_f8f6f4 v[114:117], v[130:137], v[172:179], v[114:117]
	v_mfma_f32_16x16x128_f8f6f4 v[102:105], v[138:145], v[180:187], v[102:105]
	v_mfma_f32_16x16x128_f8f6f4 v[98:101], v[130:137], v[180:187], v[98:101]
	v_mfma_f32_16x16x128_f8f6f4 v[86:89], v[138:145], v[188:195], v[86:89]
	v_mfma_f32_16x16x128_f8f6f4 v[82:85], v[130:137], v[188:195], v[82:85]
	v_mfma_f32_16x16x128_f8f6f4 v[70:73], v[138:145], v[200:207], v[70:73]
	v_mfma_f32_16x16x128_f8f6f4 v[66:69], v[130:137], v[200:207], v[66:69]
	s_setprio 0
	s_barrier
	s_add_i32 s34, s34, s96
	v_lshl_add_u64 v[196:197], v[166:167], 0, s[22:23]
	s_mov_b32 m0, s34
	s_waitcnt vmcnt(0)
	ds_read_b128 v[172:175], v171 offset:49152
	ds_read_b128 v[176:179], v171 offset:49168
	ds_read_b128 v[180:183], v171 offset:51200
	ds_read_b128 v[184:187], v171 offset:51216
	ds_read_b128 v[188:191], v171 offset:53248
	ds_read_b128 v[192:195], v171 offset:53264
	ds_read_b128 v[200:203], v171 offset:55296
	ds_read_b128 v[204:207], v171 offset:55312
	global_load_lds_dwordx4 v[196:197], off
	v_lshl_add_u64 v[196:197], v[166:167], 0, s[48:49]
	s_add_i32 m0, s34, 0x2000
	s_add_i32 s34, s35, s96
	global_load_lds_dwordx4 v[196:197], off
	v_lshl_add_u64 v[196:197], v[166:167], 0, s[26:27]
	s_mov_b32 m0, s34
	v_lshl_add_u64 v[166:167], v[166:167], 0, s[72:73]
	global_load_lds_dwordx4 v[196:197], off
	s_add_i32 m0, s34, 0x2000
	s_nop 0
	global_load_lds_dwordx4 v[166:167], off
	v_lshl_add_u64 v[166:167], v[168:169], 0, s[22:23]
	s_mov_b32 m0, s43
	s_nop 0
	global_load_lds_dwordx4 v[166:167], off
	v_lshl_add_u64 v[166:167], v[168:169], 0, s[48:49]
	s_mov_b32 m0, s44
	s_nop 0
	global_load_lds_dwordx4 v[166:167], off
	s_waitcnt vmcnt(8)
	s_waitcnt lgkmcnt(0)
	s_barrier
	s_setprio 1
	s_waitcnt lgkmcnt(0)
	v_mfma_f32_16x16x128_f8f6f4 v[62:65], v[154:161], v[172:179], v[62:65]
	v_mfma_f32_16x16x128_f8f6f4 v[58:61], v[146:153], v[172:179], v[58:61]
	v_mfma_f32_16x16x128_f8f6f4 v[46:49], v[154:161], v[180:187], v[46:49]
	v_mfma_f32_16x16x128_f8f6f4 v[42:45], v[146:153], v[180:187], v[42:45]
	v_mfma_f32_16x16x128_f8f6f4 v[30:33], v[154:161], v[188:195], v[30:33]
	v_mfma_f32_16x16x128_f8f6f4 v[26:29], v[146:153], v[188:195], v[26:29]
	v_mfma_f32_16x16x128_f8f6f4 v[14:17], v[154:161], v[200:207], v[14:17]
	v_mfma_f32_16x16x128_f8f6f4 v[10:13], v[146:153], v[200:207], v[10:13]
	s_setprio 0
	s_setprio 1
	v_mfma_f32_16x16x128_f8f6f4 v[54:57], v[138:145], v[172:179], v[54:57]
	v_mfma_f32_16x16x128_f8f6f4 v[50:53], v[130:137], v[172:179], v[50:53]
	v_mfma_f32_16x16x128_f8f6f4 v[38:41], v[138:145], v[180:187], v[38:41]
	v_mfma_f32_16x16x128_f8f6f4 v[34:37], v[130:137], v[180:187], v[34:37]
	v_mfma_f32_16x16x128_f8f6f4 v[22:25], v[138:145], v[188:195], v[22:25]
	v_mfma_f32_16x16x128_f8f6f4 v[18:21], v[130:137], v[188:195], v[18:21]
	v_mfma_f32_16x16x128_f8f6f4 v[6:9], v[138:145], v[200:207], v[6:9]
	v_mfma_f32_16x16x128_f8f6f4 v[2:5], v[130:137], v[200:207], v[2:5]
	s_setprio 0
	s_barrier
	s_add_i32 vcc_lo, vcc_lo, 2
	s_add_u32 s65, s65, 0x100
	s_addc_u32 s83, s83, 0
	s_cmp_gt_u32 vcc_lo, 5
	s_mov_b64 s[84:85], s[86:87]
	s_cbranch_scc0 .LBB0_283
	v_readlane_b32 s12, v255, 4
	v_readlane_b32 s13, v255, 5
	s_and_b64 vcc, exec, s[12:13]
	s_cbranch_vccz .LBB0_286
	s_barrier
